# dense vector phase: alpha=1 constant set once before the loop, row-sum chain starts with e0+e1 (2 fewer VALU per tile per wave), on top of nt7
# baseline (speedup 1.0000x reference)
; #define SBAR() __builtin_amdgcn_sched_barrier(0)
; __device__ __forceinline__ int v_rd_base(int lane) { return ((lane & 3) << 3) | (((lane >> 2) & 3) << 6) | (((lane >> 4) & 1) << 5) | (((lane >> 5) & 1) << 8); }
;     ...
;   float m_reg = -1e30f, l_reg = 0; f32x16 o[4] = {}; bf16x8 qr[8];
;   const bf16* Qw = Qb + (long)(wid * QBLK + r32) * qs + hi * 8;
; #pragma unroll
;   for (int d0 = 0; d0 < 8; ++d0) qr[d0] = St::ld8(Qw + d0 * 16);
;   const int vb0 = (int)(uintptr_t)V_lds + v_rd_base(lane);
;   const int kb = DIL ? i0 - 64 : 0;
;     ...
;   int krow[2], kcol[2], vrow[2], vcol[2];
; #pragma unroll
;   for (int i = 0; i < 2; ++i) { const int pc = 2 * wid + i;
;     krow[i] = pc * 4 + (lane >> 4); kcol[i] = (((lane & 15) ^ (krow[i] & 7)) << 3);
;     const int sub = pc * 2 + (lane >> 5), kk = ((sub >> 2) << 3) + ((lane & 31) >> 2);
;     vrow[i] = kk; vcol[i] = ((sub & 3) << 5) + ((lane & 3) << 3); }
;   unsigned kdo[2], vdo[2];
; #pragma unroll
;   for (int i = 0; i < 2; ++i) { kdo[i] = (unsigned)(krow[i] * (int)ks + kcol[i]); vdo[i] = (unsigned)(vrow[i] * (int)ks + vcol[i]); }
;     ...
;   int koff[4];
; #pragma unroll
;   for (int d0 = 0; d0 < 4; ++d0) koff[d0] = KSWZ(r32, (d0 * 16 + hi * 8) * 2);
;   const int kbase0 = (int)(uintptr_t)K_lds;
;     ...
;   if constexpr (DIL) {
;     const int rlo = wid >> 1;
;     for (int j = 0; j < NT; ++j) {
;       if (j + 2 < NT) DMA(j + 2, (j + 2) & 3);
;       if (j >= rlo && j <= rlo + 2) {
;         SBAR();
;         { const int kb_ = kbase0 + (j & 3) * (int)SHM_K; KFrag k0_, k1_, k2_;
;           KRD(k0_, 0, kb_); KRD(k1_, 1, kb_); KRD(k2_, 2, kb_); pA0 = f32x16{}; pA1 = f32x16{};
;           LW(4); QMM(k0_, 0); SBAR(); KRD(k0_, 3, kb_);
;           LW(4); QMM(k1_, 1); SBAR(); KRD(k1_, 4, kb_);
;           LW(4); QMM(k2_, 2); SBAR(); KRD(k2_, 5, kb_);
;           LW(4); QMM(k0_, 3); SBAR(); KRD(k0_, 6, kb_);
;           LW(4); QMM(k1_, 4); SBAR(); KRD(k1_, 7, kb_);
;           LW(4); QMM(k2_, 5); SBAR();
;           LW(2); QMM(k0_, 6); SBAR();
;           LW(0); QMM(k1_, 7); SBAR(); }
;         PSM(pA0, pA1, mnA, alA, j); RESC(alA);
;         finishSM(pA0, pA1, alA, l_reg, pa0, pa1, pa2, pa3); SBAR();
;         pv_d0(o, VBUF(j), pa0, pa1, pa2, pa3);
;       }
;       if (j + 1 < NT) ENDSTEP(j);
;     }
;   } else if constexpr (MK_PP) {
;     const bool grpB = wid >= 4;
;     ...
;     m_reg = 0.f; f32x16 negm = f32x16{};
.LBB0_55:
	s_and_b32 s12, s12, 0x3fffffc0
	s_lshr_b32 s38, s25, 7
	v_and_b32_e32 v6, 63, v212
	s_lshl_b32 s12, s12, 2
	s_and_b32 s38, s38, 1
	s_add_i32 s12, s12, 0
	v_lshlrev_b32_e32 v8, 4, v6
	s_lshl_b32 s42, s38, 22
	s_add_i32 s12, s12, 0x20000
	v_lshlrev_b32_e32 v7, 3, v6
	v_and_b32_e32 v8, 0xc0, v8
	v_lshlrev_b32_e32 v9, 1, v6
	v_and_or_b32 v8, v7, 24, v8
	v_and_b32_e32 v9, 32, v9
	v_and_b32_e32 v7, 0x100, v7
	s_cmp_lg_u32 s88, -1
	v_or3_b32 v235, v8, v9, v7
	v_lshlrev_b32_e32 v7, 4, v212
	s_cselect_b32 s38, s88, 0
	s_add_u32 s42, s42, s40
	v_and_b32_e32 v7, 0x70, v7
	s_addc_u32 s43, 0, s41
	v_bitop3_b32 v239, v0, v2, v7 bitop3:0xde
	v_bitop3_b32 v238, v3, v2, v7 bitop3:0xde
	v_bitop3_b32 v237, v4, v2, v7 bitop3:0xde
	v_bitop3_b32 v236, v5, v2, v7 bitop3:0xde
	v_add_u32_e32 v2, s15, v243
	s_add_u32 s40, s94, s42
	v_add3_u32 v2, v2, v162, v242
	v_mov_b32_e32 v3, v1
	s_addc_u32 s41, s95, s43
	v_lshlrev_b32_e32 v208, 1, v2
	v_add_u32_e32 v209, 0x80, v208
	s_add_u32 s6, s40, 0xf00c000
	s_addc_u32 s7, s41, 0
	s_add_u32 s40, s9, s42
	v_add3_u32 v2, s15, v240, v241
	s_addc_u32 s41, s21, s43
	s_addk_i32 s15, 0x200
	v_lshlrev_b32_e32 v210, 1, v2
	s_mov_b64 s[4:5], s[40:41]
	v_add3_u32 v2, s15, v240, v213
	v_mov_b32_e32 v16, v1
	v_mov_b32_e32 v17, v1
	v_add_u32_e32 v244, s38, v235
	v_cmp_gt_u32_e64 s[38:39], 32, v6
	v_lshlrev_b32_e32 v211, 1, v2
	v_mov_b32_e32 v2, v1
	v_mov_b32_e32 v4, v1
	v_mov_b32_e32 v5, v1
	v_mov_b32_e32 v6, v1
	v_mov_b32_e32 v7, v1
	v_mov_b32_e32 v8, v1
	v_mov_b32_e32 v9, v1
	v_mov_b32_e32 v10, v1
	v_mov_b32_e32 v11, v1
	v_mov_b32_e32 v12, v1
	v_mov_b32_e32 v13, v1
	v_mov_b32_e32 v14, v1
	v_mov_b32_e32 v15, v1
	v_mov_b32_e32 v240, 0
	v_mov_b64_e32 v[64:65], v[16:17]
	v_mov_b64_e32 v[48:49], v[16:17]
	v_mov_b64_e32 v[32:33], v[16:17]
	v_lshl_add_u32 v234, v232, 2, s12
	s_mov_b64 s[86:87], 0
	v_mov_b64_e32 v[62:63], v[14:15]
	v_mov_b64_e32 v[60:61], v[12:13]
	v_mov_b64_e32 v[58:59], v[10:11]
	v_mov_b64_e32 v[56:57], v[8:9]
	v_mov_b64_e32 v[54:55], v[6:7]
	v_mov_b64_e32 v[52:53], v[4:5]
	v_mov_b64_e32 v[50:51], v[2:3]
	v_mov_b64_e32 v[46:47], v[14:15]
	v_mov_b64_e32 v[44:45], v[12:13]
	v_mov_b64_e32 v[42:43], v[10:11]
	v_mov_b64_e32 v[40:41], v[8:9]
	v_mov_b64_e32 v[38:39], v[6:7]
	v_mov_b64_e32 v[36:37], v[4:5]
	v_mov_b64_e32 v[34:35], v[2:3]
	v_mov_b64_e32 v[30:31], v[14:15]
	v_mov_b64_e32 v[28:29], v[12:13]
	v_mov_b64_e32 v[26:27], v[10:11]
	v_mov_b64_e32 v[24:25], v[8:9]
	v_mov_b64_e32 v[22:23], v[6:7]
	v_mov_b64_e32 v[20:21], v[4:5]
	v_mov_b64_e32 v[18:19], v[2:3]
	v_mov_b32_e32 v241, 0
	v_mov_b32_e32 v114, 0
	v_mov_b32_e32 v115, v240
	v_mov_b32_e32 v116, v240
	v_mov_b32_e32 v117, v240
	v_mov_b32_e32 v118, v240
	v_mov_b32_e32 v119, v240
	v_mov_b32_e32 v120, v240
	v_mov_b32_e32 v121, v240
	v_mov_b32_e32 v122, v240
	v_mov_b32_e32 v123, v240
	v_mov_b32_e32 v124, v240
	v_mov_b32_e32 v125, v240
	v_mov_b32_e32 v126, v240
	v_mov_b32_e32 v127, v240
	v_mov_b32_e32 v128, v240
	v_mov_b32_e32 v129, v240
	v_mov_b32_e32 v242, 1.0

; __device__ __forceinline__ void partialSM_neg(f32x16& p0, f32x16& p1, float& m_reg, f32x16& negm, float& alpha, int bounded) {
;   if (bounded) {
;     alpha = 1.f;
; #pragma unroll
;     for (int r = 0; r < 16; ++r) p0[r] = __builtin_amdgcn_exp2f(p0[r]);
;     return;
;   }
;   float pmax = p0[0];
; #pragma unroll
;   for (int r = 1; r < 16; ++r) pmax = fmaxf(pmax, p0[r]);
; #pragma unroll
;   for (int r = 0; r < 16; ++r) pmax = fmaxf(pmax, p1[r]);
;   { auto rr = __builtin_amdgcn_permlane32_swap(__float_as_uint(pmax), __float_as_uint(pmax), false, false);
;     pmax = fmaxf(__uint_as_float(rr[0]), __uint_as_float(rr[1])); }
;   if (__builtin_expect(__all(pmax <= THR), 1)) { alpha = 1.f; }
.LBB0_58:
	s_andn2_b64 s[40:41], exec, s[80:81]
	s_andn2_b64 vcc, exec, s[80:81]
	s_cbranch_vccnz .LBB0_60
	v_max_f32_e32 v66, v99, v99
	v_max_f32_e32 v67, v98, v98
	v_max_f32_e32 v66, v67, v66
	v_max3_f32 v66, v66, v100, v101
	v_max3_f32 v66, v66, v102, v103
	v_max3_f32 v66, v66, v104, v105
	v_max3_f32 v66, v66, v106, v107
	v_max3_f32 v66, v66, v108, v109
	v_max3_f32 v66, v66, v110, v111
	v_max3_f32 v66, v66, v112, v113
	v_max3_f32 v66, v66, v82, v83
	v_max3_f32 v66, v66, v84, v85
	v_max3_f32 v66, v66, v86, v87
	v_max3_f32 v66, v66, v88, v89
	v_max3_f32 v66, v66, v90, v91
	v_max3_f32 v66, v66, v92, v93
	v_max3_f32 v66, v66, v94, v95
	v_max3_f32 v66, v66, v96, v97
	v_mov_b32_e32 v67, v66
	s_nop 1
	v_permlane32_swap_b32_e32 v66, v67
	v_max_f32_e32 v67, v67, v67
	v_max_f32_e32 v66, v66, v66
	v_max_f32_e32 v66, v66, v67
	v_cmp_ge_f32_e32 vcc, s91, v66
	s_cmp_eq_u64 vcc, exec
	v_mov_b32_e32 v242, 1.0
	s_cbranch_scc0 .LBB0_75

; #define PP_BAR(VM) do { if (VM) { asm volatile("s_waitcnt vmcnt(4) lgkmcnt(0)\n\ts_barrier" ::: "memory"); } else { asm volatile("s_waitcnt vmcnt(0) lgkmcnt(0)\n\ts_barrier" ::: "memory"); } } while (0)
; #define PP_BAR_PLAIN() asm volatile("s_waitcnt lgkmcnt(0)\n\ts_barrier" ::: "memory")
; __device__ __forceinline__ void finishSM(f32x16& p0, f32x16& p1, float alpha, float& l_reg, bf16x8& pa0, bf16x8& pa1, bf16x8& pa2, bf16x8& pa3) {
;   for (int r = 0; r < 16; ++r) p1[r] = __builtin_amdgcn_exp2f(p1[r]);
;   float ps = 0; for (int r = 0; r < 16; ++r) ps += p0[r]; for (int r = 0; r < 16; ++r) ps += p1[r];
;   { auto rr = __builtin_amdgcn_permlane32_swap(__float_as_uint(ps), __float_as_uint(ps), false, false);
;     ps = __uint_as_float(rr[0]) + __uint_as_float(rr[1]); }
;   l_reg = l_reg * alpha + ps;
;     ...
;       if (!(MK_PREB && t + 1 < NT)) { if (!grpB) PP_BAR(t + 2 < NT); else PP_BAR_PLAIN(); }
;       else if (!grpB) PP_BAR(t + 2 < NT);
;       if (!grpB && t + 3 < NT) DMA(t + 3, (t + 3) & 3);
.LBB0_65:
	v_exp_f32_e32 v98, v98
	v_exp_f32_e32 v99, v99
	v_exp_f32_e32 v100, v100
	v_exp_f32_e32 v101, v101
	v_exp_f32_e32 v102, v102
	v_exp_f32_e32 v103, v103
	v_add_f32_e32 v162, v99, v98
	v_exp_f32_e32 v104, v104
	v_add_f32_e32 v162, v100, v162
	v_exp_f32_e32 v105, v105
	v_add_f32_e32 v162, v101, v162
	v_exp_f32_e32 v106, v106
	v_add_f32_e32 v162, v102, v162
	v_exp_f32_e32 v107, v107
	v_add_f32_e32 v162, v103, v162
	v_exp_f32_e32 v108, v108
	v_add_f32_e32 v162, v104, v162
	v_exp_f32_e32 v109, v109
	v_add_f32_e32 v162, v105, v162
	v_exp_f32_e32 v110, v110
	v_add_f32_e32 v162, v106, v162
	v_exp_f32_e32 v111, v111
	v_add_f32_e32 v162, v107, v162
	v_exp_f32_e32 v112, v112
	v_add_f32_e32 v162, v108, v162
	v_exp_f32_e32 v113, v113
	v_add_f32_e32 v162, v109, v162
	v_exp_f32_e32 v82, v82
	v_add_f32_e32 v162, v110, v162
	v_exp_f32_e32 v83, v83
	v_add_f32_e32 v162, v111, v162
	v_exp_f32_e32 v84, v84
	v_add_f32_e32 v162, v112, v162
	v_exp_f32_e32 v85, v85
	v_add_f32_e32 v162, v113, v162
	v_exp_f32_e32 v86, v86
	v_add_f32_e32 v162, v82, v162
	v_exp_f32_e32 v87, v87
	v_add_f32_e32 v162, v83, v162
	v_exp_f32_e32 v88, v88
	v_add_f32_e32 v162, v84, v162
	v_exp_f32_e32 v89, v89
	v_add_f32_e32 v162, v85, v162
	v_exp_f32_e32 v90, v90
	v_add_f32_e32 v162, v86, v162
	v_exp_f32_e32 v91, v91
	v_add_f32_e32 v162, v87, v162
	v_exp_f32_e32 v92, v92
	v_add_f32_e32 v162, v88, v162
	v_exp_f32_e32 v93, v93
	v_add_f32_e32 v162, v89, v162
	v_exp_f32_e32 v94, v94
	v_add_f32_e32 v162, v90, v162
	v_exp_f32_e32 v95, v95
	v_add_f32_e32 v162, v91, v162
	v_exp_f32_e32 v96, v96
	v_add_f32_e32 v162, v92, v162
	v_exp_f32_e32 v97, v97
	v_add_f32_e32 v162, v93, v162
	v_add_f32_e32 v162, v94, v162
	v_add_f32_e32 v162, v95, v162
	v_add_f32_e32 v162, v96, v162
	v_add_f32_e32 v243, v97, v162
	v_mov_b32_e32 v245, v243
	v_cvt_pk_bf16_f32 v166, v82, v83
	s_nop 0
	v_permlane32_swap_b32_e32 v243, v245
	s_andn2_b64 s[42:43], exec, s[0:1]
	s_andn2_b64 vcc, exec, s[0:1]
	v_cvt_pk_bf16_f32 v174, v98, v99
	v_cvt_pk_bf16_f32 v175, v100, v101
	v_cvt_pk_bf16_f32 v176, v102, v103
	v_cvt_pk_bf16_f32 v177, v104, v105
	v_cvt_pk_bf16_f32 v170, v106, v107
	v_cvt_pk_bf16_f32 v171, v108, v109
	v_cvt_pk_bf16_f32 v172, v110, v111
	v_cvt_pk_bf16_f32 v173, v112, v113
	v_cvt_pk_bf16_f32 v167, v84, v85
	v_cvt_pk_bf16_f32 v168, v86, v87
	v_cvt_pk_bf16_f32 v169, v88, v89
	v_cvt_pk_bf16_f32 v162, v90, v91
	v_cvt_pk_bf16_f32 v163, v92, v93
	v_cvt_pk_bf16_f32 v164, v94, v95
	v_cvt_pk_bf16_f32 v165, v96, v97
	s_cbranch_vccnz .LBB0_67
	s_add_i32 s15, s86, 0xc000
	s_and_b32 s15, s15, 0xc000
	s_add_i32 s84, s13, s15
	s_waitcnt vmcnt(4) lgkmcnt(0)
	s_barrier
	s_mov_b32 m0, s84
	s_add_i32 s15, s14, s15
	global_load_lds_dwordx4 v210, s[16:17]
	s_mov_b32 m0, s15
	s_nop 0
	global_load_lds_dwordx4 v208, s[30:31]
	s_add_i32 m0, s84, 0x400
	s_nop 0
	global_load_lds_dwordx4 v211, s[16:17]
	s_add_i32 m0, s15, 0x400
	s_nop 0
	global_load_lds_dwordx4 v209, s[30:31]
